# hyena hidden-feature matrix stored pre-swizzled in MFMA lane order so each filter-tap load instruction reads 1 KiB contiguous instead of 64 isolated 16-byte pieces
# speedup vs baseline: 1.0368x; 1.0368x over previous
.LBB0_36:
	s_or_b64 exec, exec, s[6:7]
	v_mul_f32_e32 v7, v6, v6
	v_fmamk_f32 v8, v7, 0xb94c1982, v23
	v_fmaak_f32 v8, v7, v8, 0xbe2aaa9d
	v_mul_f32_e32 v8, v7, v8
	v_fmac_f32_e32 v6, v6, v8
	v_fmamk_f32 v8, v7, 0x37d75334, v24
	v_fmaak_f32 v8, v7, v8, 0x3d2aabf7
	v_fmaak_f32 v8, v7, v8, 0xbf000004
	v_fma_f32 v7, v7, v8, 1.0
	v_and_b32_e32 v8, 1, v0
	v_lshlrev_b32_e32 v0, 30, v0
	v_cmp_eq_u32_e64 s[6:7], 0, v8
	v_and_b32_e32 v0, 0x80000000, v0
	v_xor_b32_e32 v5, v5, v4
	v_cndmask_b32_e64 v6, v7, v6, s[6:7]
	v_xor_b32_e32 v0, v5, v0
	v_xor_b32_e32 v0, v0, v6
	v_cmp_class_f32_e64 s[6:7], v4, s42
	s_nop 1
	v_cndmask_b32_e64 v0, v29, v0, s[6:7]
	v_readlane_b32 s6, v252, 39
	v_cvt_pk_bf16_f32 v0, v0, s0
	global_store_short v[2:3], v0, off offset:112
	v_add_u32_e32 v28, s6, v28
	s_movk_i32 s6, 0x7ff
	v_cmp_lt_i32_e64 s[6:7], s6, v28
	s_or_b64 s[18:19], s[6:7], s[18:19]
	s_andn2_b64 exec, exec, s[18:19]
	s_cbranch_execz .LBB0_283

.LBB0_253:
	s_andn2_saveexec_b64 s[6:7], s[20:21]
	v_mul_f32_e64 v0, |v8|, s39
	v_rndne_f32_e32 v0, v0
	v_cvt_i32_f32_e32 v14, v0
	v_fma_f32 v18, v0, s40, |v8|
	v_fmac_f32_e32 v18, 0xb3a22168, v0
	v_fmac_f32_e32 v18, 0xa7c234c4, v0
	s_or_b64 exec, exec, s[6:7]
	v_ashrrev_i32_e32 v5, 31, v4
	v_lshlrev_b64 v[4:5], 20, v[4:5]
	v_lshl_add_u64 v[4:5], s[16:17], 0, v[4:5]
	v_and_b32_e32 v0, 31, v2
	v_sub_u32_e32 v2, v2, v0
	v_mov_b32_e32 v3, 0
	v_lshlrev_b64 v[2:3], 7, v[2:3]
	v_lshl_add_u32 v2, v0, 4, v2
	v_lshl_add_u64 v[2:3], v[4:5], 0, v[2:3]
	v_and_b32_e32 v0, 7, v16
	v_lshlrev_b32_e32 v0, 1, v0
	v_lshrrev_b32_e32 v4, 3, v16
	v_lshl_or_b32 v0, v4, 9, v0
	v_lshl_add_u64 v[2:3], v[2:3], 0, v[0:1]
	v_mul_f32_e32 v0, v18, v18
	v_fmamk_f32 v4, v0, 0xb94c1982, v23
	v_fmaak_f32 v4, v0, v4, 0xbe2aaa9d
	v_mul_f32_e32 v4, v0, v4
	v_fmac_f32_e32 v18, v18, v4
	v_fmamk_f32 v4, v0, 0x37d75334, v24
	v_fmaak_f32 v4, v0, v4, 0x3d2aabf7
	v_fmaak_f32 v4, v0, v4, 0xbf000004
	v_fma_f32 v0, v0, v4, 1.0
	v_and_b32_e32 v4, 1, v14
	v_cmp_eq_u32_e64 s[6:7], 0, v4
	v_lshlrev_b32_e32 v4, 30, v14
	v_and_b32_e32 v4, 0x80000000, v4
	v_xor_b32_e32 v5, v9, v8
	v_cndmask_b32_e64 v0, v0, v18, s[6:7]
	v_xor_b32_e32 v4, v5, v4
	v_xor_b32_e32 v0, v4, v0
	v_cmp_class_f32_e64 s[6:7], v8, s42
	v_mul_f32_e32 v4, v30, v15
	v_and_b32_e32 v5, 0x7fffffff, v4
	v_cndmask_b32_e64 v0, v29, v0, s[6:7]
	v_cvt_pk_bf16_f32 v0, v0, s0
	v_cmp_nlt_f32_e64 s[6:7], |v4|, s3
	global_store_short v[2:3], v0, off
	s_and_saveexec_b64 s[8:9], s[6:7]
	s_xor_b64 s[20:21], exec, s[8:9]
	s_cbranch_execz .LBB0_257
	v_lshrrev_b32_e32 v0, 23, v5
	v_add_u32_e32 v0, 0xffffff88, v0
	v_cmp_lt_u32_e64 s[6:7], 63, v0
	s_nop 1
	v_cndmask_b32_e64 v8, 0, v25, s[6:7]
	v_add_u32_e32 v0, v8, v0
	v_cmp_lt_u32_e64 s[8:9], 31, v0
	s_nop 1
	v_cndmask_b32_e64 v8, 0, v26, s[8:9]
	v_add_u32_e32 v0, v8, v0
	v_cmp_lt_u32_e64 s[10:11], 31, v0
	s_nop 1
	v_cndmask_b32_e64 v8, 0, v26, s[10:11]
	v_add_u32_e32 v31, v8, v0
	v_and_b32_e32 v0, 0x7fffff, v5
	v_or_b32_e32 v36, 0x800000, v0
	v_mad_u64_u32 v[8:9], s[12:13], v36, s30, 0
	v_mov_b32_e32 v0, v9
	v_mad_u64_u32 v[14:15], s[12:13], v36, s31, v[0:1]
	v_mov_b32_e32 v0, v15
	v_mad_u64_u32 v[18:19], s[12:13], v36, s33, v[0:1]
	v_mov_b32_e32 v0, v19
	v_mad_u64_u32 v[20:21], s[12:13], v36, s34, v[0:1]
	v_mov_b32_e32 v0, v21
	v_mad_u64_u32 v[32:33], s[12:13], v36, s35, v[0:1]
	v_mov_b32_e32 v0, v33
	v_mad_u64_u32 v[34:35], s[12:13], v36, s36, v[0:1]
	v_mov_b32_e32 v0, v35
	v_mad_u64_u32 v[36:37], s[12:13], v36, s37, v[0:1]
	v_cndmask_b32_e64 v9, v34, v20, s[6:7]
	v_cndmask_b32_e64 v0, v36, v32, s[6:7]
	v_cndmask_b32_e64 v19, v37, v34, s[6:7]
	v_cndmask_b32_e64 v15, v0, v9, s[8:9]
	v_cndmask_b32_e64 v0, v19, v0, s[8:9]
	v_cndmask_b32_e64 v19, v32, v18, s[6:7]
	v_cndmask_b32_e64 v9, v9, v19, s[8:9]
	v_cndmask_b32_e64 v14, v20, v14, s[6:7]
	v_cndmask_b32_e64 v0, v0, v15, s[10:11]
	v_cndmask_b32_e64 v15, v15, v9, s[10:11]
	v_sub_u32_e32 v21, 32, v31
	v_cndmask_b32_e64 v19, v19, v14, s[8:9]
	v_alignbit_b32 v32, v0, v15, v21
	v_cmp_eq_u32_e64 s[12:13], 0, v31
	v_cndmask_b32_e64 v9, v9, v19, s[10:11]
	v_cndmask_b32_e64 v8, v18, v8, s[6:7]
	v_cndmask_b32_e64 v0, v32, v0, s[12:13]
	v_alignbit_b32 v20, v15, v9, v21
	v_cndmask_b32_e64 v8, v14, v8, s[8:9]
	v_cndmask_b32_e64 v15, v20, v15, s[12:13]
	v_bfe_u32 v32, v0, 29, 1
	v_cndmask_b32_e64 v8, v19, v8, s[10:11]
	v_alignbit_b32 v20, v0, v15, 30
	v_sub_u32_e32 v33, 0, v32
	v_alignbit_b32 v14, v9, v8, v21
	v_xor_b32_e32 v20, v20, v33
	v_cndmask_b32_e64 v9, v14, v9, s[12:13]
	v_alignbit_b32 v14, v15, v9, 30
	v_ffbh_u32_e32 v15, v20
	v_min_u32_e32 v15, 32, v15
	v_alignbit_b32 v8, v9, v8, 30
	v_xor_b32_e32 v14, v14, v33
	v_sub_u32_e32 v18, 31, v15
	v_xor_b32_e32 v8, v8, v33
	v_alignbit_b32 v19, v20, v14, v18
	v_alignbit_b32 v8, v14, v8, v18
	v_alignbit_b32 v9, v19, v8, 9
	v_ffbh_u32_e32 v14, v9
	v_min_u32_e32 v14, 32, v14
	v_lshrrev_b32_e32 v31, 29, v0
	v_not_b32_e32 v18, v14
	v_alignbit_b32 v8, v9, v8, v18
	v_lshlrev_b32_e32 v9, 31, v31
	v_or_b32_e32 v18, 0x33000000, v9
	v_add_lshl_u32 v14, v14, v15, 23
	v_lshrrev_b32_e32 v8, 9, v8
	v_sub_u32_e32 v14, v18, v14
	v_or_b32_e32 v9, 0.5, v9
	v_lshlrev_b32_e32 v15, 23, v15
	v_or_b32_e32 v8, v14, v8
	v_lshrrev_b32_e32 v14, 9, v19
	v_sub_u32_e32 v9, v9, v15
	v_or_b32_e32 v9, v14, v9
	v_mul_f32_e32 v14, 0x3fc90fda, v9
	v_fma_f32 v15, v9, s38, -v14
	v_fmac_f32_e32 v15, 0x33a22168, v9
	v_fmac_f32_e32 v15, 0x3fc90fda, v8
	v_lshrrev_b32_e32 v0, 30, v0
	v_add_f32_e32 v8, v14, v15
	v_add_u32_e32 v0, v32, v0
.LBB0_257:
	s_andn2_saveexec_b64 s[6:7], s[20:21]
	v_mul_f32_e64 v0, |v4|, s39
	v_rndne_f32_e32 v9, v0
	v_cvt_i32_f32_e32 v0, v9
	v_fma_f32 v8, v9, s40, |v4|
	v_fmac_f32_e32 v8, 0xb3a22168, v9
	v_fmac_f32_e32 v8, 0xa7c234c4, v9
	s_or_b64 exec, exec, s[6:7]
	v_mul_f32_e32 v9, v8, v8
	v_fmamk_f32 v14, v9, 0xb94c1982, v23
	v_fmaak_f32 v14, v9, v14, 0xbe2aaa9d
	v_mul_f32_e32 v14, v9, v14
	v_fmac_f32_e32 v8, v8, v14
	v_fmamk_f32 v14, v9, 0x37d75334, v24
	v_fmaak_f32 v14, v9, v14, 0x3d2aabf7
	v_fmaak_f32 v14, v9, v14, 0xbf000004
	v_fma_f32 v9, v9, v14, 1.0
	v_and_b32_e32 v14, 1, v0
	v_lshlrev_b32_e32 v0, 30, v0
	v_cmp_eq_u32_e64 s[6:7], 0, v14
	v_and_b32_e32 v0, 0x80000000, v0
	v_xor_b32_e32 v5, v5, v4
	v_cndmask_b32_e64 v8, v9, v8, s[6:7]
	v_xor_b32_e32 v0, v5, v0
	v_xor_b32_e32 v0, v0, v8
	v_cmp_class_f32_e64 s[6:7], v4, s42
	v_mul_f32_e32 v4, v30, v12
	v_and_b32_e32 v5, 0x7fffffff, v4
	v_cndmask_b32_e64 v0, v29, v0, s[6:7]
	v_cvt_pk_bf16_f32 v0, v0, s0
	v_cmp_nlt_f32_e64 s[6:7], |v4|, s3
	global_store_short v[2:3], v0, off offset:16
	s_and_saveexec_b64 s[8:9], s[6:7]
	s_xor_b64 s[20:21], exec, s[8:9]
	s_cbranch_execz .LBB0_261
	v_lshrrev_b32_e32 v0, 23, v5
	v_add_u32_e32 v0, 0xffffff88, v0
	v_cmp_lt_u32_e64 s[6:7], 63, v0
	s_nop 1
	v_cndmask_b32_e64 v8, 0, v25, s[6:7]
	v_add_u32_e32 v0, v8, v0
	v_cmp_lt_u32_e64 s[8:9], 31, v0
	s_nop 1
	v_cndmask_b32_e64 v8, 0, v26, s[8:9]
	v_add_u32_e32 v0, v8, v0
	v_cmp_lt_u32_e64 s[10:11], 31, v0
	s_nop 1
	v_cndmask_b32_e64 v8, 0, v26, s[10:11]
	v_add_u32_e32 v12, v8, v0
	v_and_b32_e32 v0, 0x7fffff, v5
	v_or_b32_e32 v31, 0x800000, v0
	v_mad_u64_u32 v[8:9], s[12:13], v31, s30, 0
	v_mov_b32_e32 v0, v9
	v_mad_u64_u32 v[14:15], s[12:13], v31, s31, v[0:1]
	v_mov_b32_e32 v0, v15
	v_mad_u64_u32 v[18:19], s[12:13], v31, s33, v[0:1]
	v_mov_b32_e32 v0, v19
	v_mad_u64_u32 v[20:21], s[12:13], v31, s34, v[0:1]
	v_mov_b32_e32 v0, v21
	v_mad_u64_u32 v[32:33], s[12:13], v31, s35, v[0:1]
	v_mov_b32_e32 v0, v33
	v_mad_u64_u32 v[34:35], s[12:13], v31, s36, v[0:1]
	v_mov_b32_e32 v0, v35
	v_mad_u64_u32 v[36:37], s[12:13], v31, s37, v[0:1]
	v_cndmask_b32_e64 v9, v34, v20, s[6:7]
	v_cndmask_b32_e64 v0, v36, v32, s[6:7]
	v_cndmask_b32_e64 v19, v37, v34, s[6:7]
	v_cndmask_b32_e64 v15, v0, v9, s[8:9]
	v_cndmask_b32_e64 v0, v19, v0, s[8:9]
	v_cndmask_b32_e64 v19, v32, v18, s[6:7]
	v_cndmask_b32_e64 v9, v9, v19, s[8:9]
	v_sub_u32_e32 v21, 32, v12
	v_cmp_eq_u32_e64 s[12:13], 0, v12
	v_cndmask_b32_e64 v12, v20, v14, s[6:7]
	v_cndmask_b32_e64 v0, v0, v15, s[10:11]
	v_cndmask_b32_e64 v15, v15, v9, s[10:11]
	v_cndmask_b32_e64 v14, v19, v12, s[8:9]
	v_alignbit_b32 v31, v0, v15, v21
	v_cndmask_b32_e64 v9, v9, v14, s[10:11]
	v_cndmask_b32_e64 v0, v31, v0, s[12:13]
	v_alignbit_b32 v19, v15, v9, v21
	v_cndmask_b32_e64 v8, v18, v8, s[6:7]
	v_cndmask_b32_e64 v15, v19, v15, s[12:13]
	v_bfe_u32 v31, v0, 29, 1
	v_cndmask_b32_e64 v8, v12, v8, s[8:9]
	v_alignbit_b32 v19, v0, v15, 30
	v_sub_u32_e32 v32, 0, v31
	v_cndmask_b32_e64 v8, v14, v8, s[10:11]
	v_xor_b32_e32 v19, v19, v32
	v_alignbit_b32 v12, v9, v8, v21
	v_cndmask_b32_e64 v9, v12, v9, s[12:13]
	v_ffbh_u32_e32 v14, v19
	v_alignbit_b32 v12, v15, v9, 30
	v_min_u32_e32 v14, 32, v14
	v_alignbit_b32 v8, v9, v8, 30
	v_xor_b32_e32 v12, v12, v32
	v_sub_u32_e32 v15, 31, v14
	v_xor_b32_e32 v8, v8, v32
	v_alignbit_b32 v18, v19, v12, v15
	v_alignbit_b32 v8, v12, v8, v15
	v_alignbit_b32 v9, v18, v8, 9
	v_ffbh_u32_e32 v12, v9
	v_min_u32_e32 v12, 32, v12
	v_lshrrev_b32_e32 v20, 29, v0
	v_not_b32_e32 v15, v12
	v_alignbit_b32 v8, v9, v8, v15
	v_lshlrev_b32_e32 v9, 31, v20
	v_or_b32_e32 v15, 0x33000000, v9
	v_add_lshl_u32 v12, v12, v14, 23
	v_lshrrev_b32_e32 v8, 9, v8
	v_sub_u32_e32 v12, v15, v12
	v_or_b32_e32 v9, 0.5, v9
	v_lshlrev_b32_e32 v14, 23, v14
	v_or_b32_e32 v8, v12, v8
	v_lshrrev_b32_e32 v12, 9, v18
	v_sub_u32_e32 v9, v9, v14
	v_or_b32_e32 v9, v12, v9
	v_mul_f32_e32 v12, 0x3fc90fda, v9
	v_fma_f32 v14, v9, s38, -v12
	v_fmac_f32_e32 v14, 0x33a22168, v9
	v_fmac_f32_e32 v14, 0x3fc90fda, v8
	v_lshrrev_b32_e32 v0, 30, v0
	v_add_f32_e32 v8, v12, v14
	v_add_u32_e32 v0, v31, v0
.LBB0_261:
	s_andn2_saveexec_b64 s[6:7], s[20:21]
	v_mul_f32_e64 v0, |v4|, s39
	v_rndne_f32_e32 v9, v0
	v_cvt_i32_f32_e32 v0, v9
	v_fma_f32 v8, v9, s40, |v4|
	v_fmac_f32_e32 v8, 0xb3a22168, v9
	v_fmac_f32_e32 v8, 0xa7c234c4, v9
	s_or_b64 exec, exec, s[6:7]
	v_mul_f32_e32 v9, v8, v8
	v_fmamk_f32 v12, v9, 0xb94c1982, v23
	v_fmaak_f32 v12, v9, v12, 0xbe2aaa9d
	v_mul_f32_e32 v12, v9, v12
	v_fmac_f32_e32 v8, v8, v12
	v_fmamk_f32 v12, v9, 0x37d75334, v24
	v_fmaak_f32 v12, v9, v12, 0x3d2aabf7
	v_fmaak_f32 v12, v9, v12, 0xbf000004
	v_fma_f32 v9, v9, v12, 1.0
	v_and_b32_e32 v12, 1, v0
	v_lshlrev_b32_e32 v0, 30, v0
	v_cmp_eq_u32_e64 s[6:7], 0, v12
	v_and_b32_e32 v0, 0x80000000, v0
	v_xor_b32_e32 v5, v5, v4
	v_cndmask_b32_e64 v8, v9, v8, s[6:7]
	v_xor_b32_e32 v0, v5, v0
	v_xor_b32_e32 v0, v0, v8
	v_cmp_class_f32_e64 s[6:7], v4, s42
	v_mul_f32_e32 v4, v30, v13
	v_and_b32_e32 v5, 0x7fffffff, v4
	v_cndmask_b32_e64 v0, v29, v0, s[6:7]
	v_cvt_pk_bf16_f32 v0, v0, s0
	v_cmp_nlt_f32_e64 s[6:7], |v4|, s3
	global_store_short v[2:3], v0, off offset:32
	s_and_saveexec_b64 s[8:9], s[6:7]
	s_xor_b64 s[20:21], exec, s[8:9]
	s_cbranch_execz .LBB0_265
	v_lshrrev_b32_e32 v0, 23, v5
	v_add_u32_e32 v0, 0xffffff88, v0
	v_cmp_lt_u32_e64 s[6:7], 63, v0
	s_nop 1
	v_cndmask_b32_e64 v8, 0, v25, s[6:7]
	v_add_u32_e32 v0, v8, v0
	v_cmp_lt_u32_e64 s[8:9], 31, v0
	s_nop 1
	v_cndmask_b32_e64 v8, 0, v26, s[8:9]
	v_add_u32_e32 v0, v8, v0
	v_cmp_lt_u32_e64 s[10:11], 31, v0
	s_nop 1
	v_cndmask_b32_e64 v8, 0, v26, s[10:11]
	v_add_u32_e32 v31, v8, v0
	v_and_b32_e32 v0, 0x7fffff, v5
	v_or_b32_e32 v34, 0x800000, v0
	v_mad_u64_u32 v[8:9], s[12:13], v34, s30, 0
	v_mov_b32_e32 v0, v9
	v_mad_u64_u32 v[12:13], s[12:13], v34, s31, v[0:1]
	v_mov_b32_e32 v0, v13
	v_mad_u64_u32 v[14:15], s[12:13], v34, s33, v[0:1]
	v_mov_b32_e32 v0, v15
	v_mad_u64_u32 v[18:19], s[12:13], v34, s34, v[0:1]
	v_mov_b32_e32 v0, v19
	v_mad_u64_u32 v[20:21], s[12:13], v34, s35, v[0:1]
	v_mov_b32_e32 v0, v21
	v_mad_u64_u32 v[32:33], s[12:13], v34, s36, v[0:1]
	v_mov_b32_e32 v0, v33
	v_mad_u64_u32 v[34:35], s[12:13], v34, s37, v[0:1]
	v_cndmask_b32_e64 v9, v32, v18, s[6:7]
	v_cndmask_b32_e64 v0, v34, v20, s[6:7]
	v_cndmask_b32_e64 v15, v35, v32, s[6:7]
	v_cndmask_b32_e64 v13, v0, v9, s[8:9]
	v_cndmask_b32_e64 v0, v15, v0, s[8:9]
	v_cndmask_b32_e64 v15, v20, v14, s[6:7]
	v_cndmask_b32_e64 v9, v9, v15, s[8:9]
	v_cndmask_b32_e64 v12, v18, v12, s[6:7]
	v_cndmask_b32_e64 v0, v0, v13, s[10:11]
	v_cndmask_b32_e64 v13, v13, v9, s[10:11]
	v_sub_u32_e32 v19, 32, v31
	v_cndmask_b32_e64 v15, v15, v12, s[8:9]
	v_alignbit_b32 v20, v0, v13, v19
	v_cmp_eq_u32_e64 s[12:13], 0, v31
	v_cndmask_b32_e64 v9, v9, v15, s[10:11]
	v_cndmask_b32_e64 v8, v14, v8, s[6:7]
	v_cndmask_b32_e64 v0, v20, v0, s[12:13]
	v_alignbit_b32 v18, v13, v9, v19
	v_cndmask_b32_e64 v8, v12, v8, s[8:9]
	v_cndmask_b32_e64 v13, v18, v13, s[12:13]
	v_bfe_u32 v21, v0, 29, 1
	v_cndmask_b32_e64 v8, v15, v8, s[10:11]
	v_alignbit_b32 v18, v0, v13, 30
	v_sub_u32_e32 v31, 0, v21
	v_alignbit_b32 v12, v9, v8, v19
	v_xor_b32_e32 v18, v18, v31
	v_cndmask_b32_e64 v9, v12, v9, s[12:13]
	v_alignbit_b32 v12, v13, v9, 30
	v_ffbh_u32_e32 v13, v18
	v_min_u32_e32 v13, 32, v13
	v_alignbit_b32 v8, v9, v8, 30
	v_xor_b32_e32 v12, v12, v31
	v_sub_u32_e32 v14, 31, v13
	v_xor_b32_e32 v8, v8, v31
	v_alignbit_b32 v15, v18, v12, v14
	v_alignbit_b32 v8, v12, v8, v14
	v_alignbit_b32 v9, v15, v8, 9
	v_ffbh_u32_e32 v12, v9
	v_min_u32_e32 v12, 32, v12
	v_lshrrev_b32_e32 v20, 29, v0
	v_not_b32_e32 v14, v12
	v_alignbit_b32 v8, v9, v8, v14
	v_lshlrev_b32_e32 v9, 31, v20
	v_or_b32_e32 v14, 0x33000000, v9
	v_add_lshl_u32 v12, v12, v13, 23
	v_lshrrev_b32_e32 v8, 9, v8
	v_sub_u32_e32 v12, v14, v12
	v_or_b32_e32 v9, 0.5, v9
	v_lshlrev_b32_e32 v13, 23, v13
	v_or_b32_e32 v8, v12, v8
	v_lshrrev_b32_e32 v12, 9, v15
	v_sub_u32_e32 v9, v9, v13
	v_or_b32_e32 v9, v12, v9
	v_mul_f32_e32 v12, 0x3fc90fda, v9
	v_fma_f32 v13, v9, s38, -v12
	v_fmac_f32_e32 v13, 0x33a22168, v9
	v_fmac_f32_e32 v13, 0x3fc90fda, v8
	v_lshrrev_b32_e32 v0, 30, v0
	v_add_f32_e32 v8, v12, v13
	v_add_u32_e32 v0, v21, v0
.LBB0_265:
	s_andn2_saveexec_b64 s[6:7], s[20:21]
	v_mul_f32_e64 v0, |v4|, s39
	v_rndne_f32_e32 v9, v0
	v_cvt_i32_f32_e32 v0, v9
	v_fma_f32 v8, v9, s40, |v4|
	v_fmac_f32_e32 v8, 0xb3a22168, v9
	v_fmac_f32_e32 v8, 0xa7c234c4, v9
	s_or_b64 exec, exec, s[6:7]
	v_mul_f32_e32 v9, v8, v8
	v_fmamk_f32 v12, v9, 0xb94c1982, v23
	v_fmaak_f32 v12, v9, v12, 0xbe2aaa9d
	v_mul_f32_e32 v12, v9, v12
	v_fmac_f32_e32 v8, v8, v12
	v_fmamk_f32 v12, v9, 0x37d75334, v24
	v_fmaak_f32 v12, v9, v12, 0x3d2aabf7
	v_fmaak_f32 v12, v9, v12, 0xbf000004
	v_fma_f32 v9, v9, v12, 1.0
	v_and_b32_e32 v12, 1, v0
	v_lshlrev_b32_e32 v0, 30, v0
	v_cmp_eq_u32_e64 s[6:7], 0, v12
	v_and_b32_e32 v0, 0x80000000, v0
	v_xor_b32_e32 v5, v5, v4
	v_cndmask_b32_e64 v8, v9, v8, s[6:7]
	v_xor_b32_e32 v0, v5, v0
	v_xor_b32_e32 v0, v0, v8
	v_cmp_class_f32_e64 s[6:7], v4, s42
	v_mul_f32_e32 v4, v30, v10
	v_and_b32_e32 v5, 0x7fffffff, v4
	v_cndmask_b32_e64 v0, v29, v0, s[6:7]
	v_cvt_pk_bf16_f32 v0, v0, s0
	v_cmp_nlt_f32_e64 s[6:7], |v4|, s3
	global_store_short v[2:3], v0, off offset:48
	s_and_saveexec_b64 s[8:9], s[6:7]
	s_xor_b64 s[20:21], exec, s[8:9]
	s_cbranch_execz .LBB0_269
	v_lshrrev_b32_e32 v0, 23, v5
	v_add_u32_e32 v0, 0xffffff88, v0
	v_cmp_lt_u32_e64 s[6:7], 63, v0
	s_nop 1
	v_cndmask_b32_e64 v8, 0, v25, s[6:7]
	v_add_u32_e32 v0, v8, v0
	v_cmp_lt_u32_e64 s[8:9], 31, v0
	s_nop 1
	v_cndmask_b32_e64 v8, 0, v26, s[8:9]
	v_add_u32_e32 v0, v8, v0
	v_cmp_lt_u32_e64 s[10:11], 31, v0
	s_nop 1
	v_cndmask_b32_e64 v8, 0, v26, s[10:11]
	v_add_u32_e32 v10, v8, v0
	v_and_b32_e32 v0, 0x7fffff, v5
	v_or_b32_e32 v31, 0x800000, v0
	v_mad_u64_u32 v[8:9], s[12:13], v31, s30, 0
	v_mov_b32_e32 v0, v9
	v_mad_u64_u32 v[12:13], s[12:13], v31, s31, v[0:1]
	v_mov_b32_e32 v0, v13
	v_mad_u64_u32 v[14:15], s[12:13], v31, s33, v[0:1]
	v_mov_b32_e32 v0, v15
	v_mad_u64_u32 v[18:19], s[12:13], v31, s34, v[0:1]
	v_mov_b32_e32 v0, v19
	v_mad_u64_u32 v[20:21], s[12:13], v31, s35, v[0:1]
	v_mov_b32_e32 v0, v21
	v_mad_u64_u32 v[32:33], s[12:13], v31, s36, v[0:1]
	v_mov_b32_e32 v0, v33
	v_mad_u64_u32 v[34:35], s[12:13], v31, s37, v[0:1]
	v_cndmask_b32_e64 v9, v32, v18, s[6:7]
	v_cndmask_b32_e64 v0, v34, v20, s[6:7]
	v_cndmask_b32_e64 v15, v35, v32, s[6:7]
	v_cndmask_b32_e64 v13, v0, v9, s[8:9]
	v_cndmask_b32_e64 v0, v15, v0, s[8:9]
	v_cndmask_b32_e64 v15, v20, v14, s[6:7]
	v_cndmask_b32_e64 v9, v9, v15, s[8:9]
	v_sub_u32_e32 v19, 32, v10
	v_cmp_eq_u32_e64 s[12:13], 0, v10
	v_cndmask_b32_e64 v10, v18, v12, s[6:7]
	v_cndmask_b32_e64 v0, v0, v13, s[10:11]
	v_cndmask_b32_e64 v13, v13, v9, s[10:11]
	v_cndmask_b32_e64 v12, v15, v10, s[8:9]
	v_alignbit_b32 v20, v0, v13, v19
	v_cndmask_b32_e64 v9, v9, v12, s[10:11]
	v_cndmask_b32_e64 v0, v20, v0, s[12:13]
	v_alignbit_b32 v15, v13, v9, v19
	v_cndmask_b32_e64 v8, v14, v8, s[6:7]
	v_cndmask_b32_e64 v13, v15, v13, s[12:13]
	v_bfe_u32 v20, v0, 29, 1
	v_cndmask_b32_e64 v8, v10, v8, s[8:9]
	v_alignbit_b32 v15, v0, v13, 30
	v_sub_u32_e32 v21, 0, v20
	v_cndmask_b32_e64 v8, v12, v8, s[10:11]
	v_xor_b32_e32 v15, v15, v21
	v_alignbit_b32 v10, v9, v8, v19
	v_cndmask_b32_e64 v9, v10, v9, s[12:13]
	v_ffbh_u32_e32 v12, v15
	v_alignbit_b32 v10, v13, v9, 30
	v_min_u32_e32 v12, 32, v12
	v_alignbit_b32 v8, v9, v8, 30
	v_xor_b32_e32 v10, v10, v21
	v_sub_u32_e32 v13, 31, v12
	v_xor_b32_e32 v8, v8, v21
	v_alignbit_b32 v14, v15, v10, v13
	v_alignbit_b32 v8, v10, v8, v13
	v_alignbit_b32 v9, v14, v8, 9
	v_ffbh_u32_e32 v10, v9
	v_min_u32_e32 v10, 32, v10
	v_lshrrev_b32_e32 v18, 29, v0
	v_not_b32_e32 v13, v10
	v_alignbit_b32 v8, v9, v8, v13
	v_lshlrev_b32_e32 v9, 31, v18
	v_or_b32_e32 v13, 0x33000000, v9
	v_add_lshl_u32 v10, v10, v12, 23
	v_lshrrev_b32_e32 v8, 9, v8
	v_sub_u32_e32 v10, v13, v10
	v_or_b32_e32 v9, 0.5, v9
	v_lshlrev_b32_e32 v12, 23, v12
	v_or_b32_e32 v8, v10, v8
	v_lshrrev_b32_e32 v10, 9, v14
	v_sub_u32_e32 v9, v9, v12
	v_or_b32_e32 v9, v10, v9
	v_mul_f32_e32 v10, 0x3fc90fda, v9
	v_fma_f32 v12, v9, s38, -v10
	v_fmac_f32_e32 v12, 0x33a22168, v9
	v_fmac_f32_e32 v12, 0x3fc90fda, v8
	v_lshrrev_b32_e32 v0, 30, v0
	v_add_f32_e32 v8, v10, v12
	v_add_u32_e32 v0, v20, v0
.LBB0_269:
	s_andn2_saveexec_b64 s[6:7], s[20:21]
	v_mul_f32_e64 v0, |v4|, s39
	v_rndne_f32_e32 v9, v0
	v_cvt_i32_f32_e32 v0, v9
	v_fma_f32 v8, v9, s40, |v4|
	v_fmac_f32_e32 v8, 0xb3a22168, v9
	v_fmac_f32_e32 v8, 0xa7c234c4, v9
	s_or_b64 exec, exec, s[6:7]
	v_mul_f32_e32 v9, v8, v8
	v_fmamk_f32 v10, v9, 0xb94c1982, v23
	v_fmaak_f32 v10, v9, v10, 0xbe2aaa9d
	v_mul_f32_e32 v10, v9, v10
	v_fmac_f32_e32 v8, v8, v10
	v_fmamk_f32 v10, v9, 0x37d75334, v24
	v_fmaak_f32 v10, v9, v10, 0x3d2aabf7
	v_fmaak_f32 v10, v9, v10, 0xbf000004
	v_fma_f32 v9, v9, v10, 1.0
	v_and_b32_e32 v10, 1, v0
	v_lshlrev_b32_e32 v0, 30, v0
	v_cmp_eq_u32_e64 s[6:7], 0, v10
	v_and_b32_e32 v0, 0x80000000, v0
	v_xor_b32_e32 v5, v5, v4
	v_cndmask_b32_e64 v8, v9, v8, s[6:7]
	v_xor_b32_e32 v0, v5, v0
	v_xor_b32_e32 v0, v0, v8
	v_cmp_class_f32_e64 s[6:7], v4, s42
	v_mul_f32_e32 v4, v30, v11
	v_and_b32_e32 v5, 0x7fffffff, v4
	v_cndmask_b32_e64 v0, v29, v0, s[6:7]
	v_cvt_pk_bf16_f32 v0, v0, s0
	v_cmp_nlt_f32_e64 s[6:7], |v4|, s3
	global_store_short v[2:3], v0, off offset:64
	s_and_saveexec_b64 s[8:9], s[6:7]
	s_xor_b64 s[20:21], exec, s[8:9]
	s_cbranch_execz .LBB0_273
	v_lshrrev_b32_e32 v0, 23, v5
	v_add_u32_e32 v0, 0xffffff88, v0
	v_cmp_lt_u32_e64 s[6:7], 63, v0
	s_nop 1
	v_cndmask_b32_e64 v8, 0, v25, s[6:7]
	v_add_u32_e32 v0, v8, v0
	v_cmp_lt_u32_e64 s[8:9], 31, v0
	s_nop 1
	v_cndmask_b32_e64 v8, 0, v26, s[8:9]
	v_add_u32_e32 v0, v8, v0
	v_cmp_lt_u32_e64 s[10:11], 31, v0
	s_nop 1
	v_cndmask_b32_e64 v8, 0, v26, s[10:11]
	v_add_u32_e32 v31, v8, v0
	v_and_b32_e32 v0, 0x7fffff, v5
	v_or_b32_e32 v32, 0x800000, v0
	v_mad_u64_u32 v[8:9], s[12:13], v32, s30, 0
	v_mov_b32_e32 v0, v9
	v_mad_u64_u32 v[10:11], s[12:13], v32, s31, v[0:1]
	v_mov_b32_e32 v0, v11
	v_mad_u64_u32 v[12:13], s[12:13], v32, s33, v[0:1]
	v_mov_b32_e32 v0, v13
	v_mad_u64_u32 v[14:15], s[12:13], v32, s34, v[0:1]
	v_mov_b32_e32 v0, v15
	v_mad_u64_u32 v[18:19], s[12:13], v32, s35, v[0:1]
	v_mov_b32_e32 v0, v19
	v_mad_u64_u32 v[20:21], s[12:13], v32, s36, v[0:1]
	v_mov_b32_e32 v0, v21
	v_mad_u64_u32 v[32:33], s[12:13], v32, s37, v[0:1]
	v_cndmask_b32_e64 v9, v20, v14, s[6:7]
	v_cndmask_b32_e64 v0, v32, v18, s[6:7]
	v_cndmask_b32_e64 v13, v33, v20, s[6:7]
	v_cndmask_b32_e64 v11, v0, v9, s[8:9]
	v_cndmask_b32_e64 v0, v13, v0, s[8:9]
	v_cndmask_b32_e64 v13, v18, v12, s[6:7]
	v_cndmask_b32_e64 v9, v9, v13, s[8:9]
	v_cndmask_b32_e64 v10, v14, v10, s[6:7]
	v_cndmask_b32_e64 v0, v0, v11, s[10:11]
	v_cndmask_b32_e64 v11, v11, v9, s[10:11]
	v_sub_u32_e32 v15, 32, v31
	v_cndmask_b32_e64 v13, v13, v10, s[8:9]
	v_alignbit_b32 v18, v0, v11, v15
	v_cmp_eq_u32_e64 s[12:13], 0, v31
	v_cndmask_b32_e64 v9, v9, v13, s[10:11]
	v_cndmask_b32_e64 v8, v12, v8, s[6:7]
	v_cndmask_b32_e64 v0, v18, v0, s[12:13]
	v_alignbit_b32 v14, v11, v9, v15
	v_cndmask_b32_e64 v8, v10, v8, s[8:9]
	v_cndmask_b32_e64 v11, v14, v11, s[12:13]
	v_bfe_u32 v19, v0, 29, 1
	v_cndmask_b32_e64 v8, v13, v8, s[10:11]
	v_alignbit_b32 v14, v0, v11, 30
	v_sub_u32_e32 v20, 0, v19
	v_alignbit_b32 v10, v9, v8, v15
	v_xor_b32_e32 v14, v14, v20
	v_cndmask_b32_e64 v9, v10, v9, s[12:13]
	v_alignbit_b32 v10, v11, v9, 30
	v_ffbh_u32_e32 v11, v14
	v_min_u32_e32 v11, 32, v11
	v_alignbit_b32 v8, v9, v8, 30
	v_xor_b32_e32 v10, v10, v20
	v_sub_u32_e32 v12, 31, v11
	v_xor_b32_e32 v8, v8, v20
	v_alignbit_b32 v13, v14, v10, v12
	v_alignbit_b32 v8, v10, v8, v12
	v_alignbit_b32 v9, v13, v8, 9
	v_ffbh_u32_e32 v10, v9
	v_min_u32_e32 v10, 32, v10
	v_lshrrev_b32_e32 v18, 29, v0
	v_not_b32_e32 v12, v10
	v_alignbit_b32 v8, v9, v8, v12
	v_lshlrev_b32_e32 v9, 31, v18
	v_or_b32_e32 v12, 0x33000000, v9
	v_add_lshl_u32 v10, v10, v11, 23
	v_lshrrev_b32_e32 v8, 9, v8
	v_sub_u32_e32 v10, v12, v10
	v_or_b32_e32 v9, 0.5, v9
	v_lshlrev_b32_e32 v11, 23, v11
	v_or_b32_e32 v8, v10, v8
	v_lshrrev_b32_e32 v10, 9, v13
	v_sub_u32_e32 v9, v9, v11
	v_or_b32_e32 v9, v10, v9
	v_mul_f32_e32 v10, 0x3fc90fda, v9
	v_fma_f32 v11, v9, s38, -v10
	v_fmac_f32_e32 v11, 0x33a22168, v9
	v_fmac_f32_e32 v11, 0x3fc90fda, v8
	v_lshrrev_b32_e32 v0, 30, v0
	v_add_f32_e32 v8, v10, v11
	v_add_u32_e32 v0, v19, v0
.LBB0_273:
	s_andn2_saveexec_b64 s[6:7], s[20:21]
	v_mul_f32_e64 v0, |v4|, s39
	v_rndne_f32_e32 v9, v0
	v_cvt_i32_f32_e32 v0, v9
	v_fma_f32 v8, v9, s40, |v4|
	v_fmac_f32_e32 v8, 0xb3a22168, v9
	v_fmac_f32_e32 v8, 0xa7c234c4, v9
	s_or_b64 exec, exec, s[6:7]
	v_mul_f32_e32 v9, v8, v8
	v_fmamk_f32 v10, v9, 0xb94c1982, v23
	v_fmaak_f32 v10, v9, v10, 0xbe2aaa9d
	v_mul_f32_e32 v10, v9, v10
	v_fmac_f32_e32 v8, v8, v10
	v_fmamk_f32 v10, v9, 0x37d75334, v24
	v_fmaak_f32 v10, v9, v10, 0x3d2aabf7
	v_fmaak_f32 v10, v9, v10, 0xbf000004
	v_fma_f32 v9, v9, v10, 1.0
	v_and_b32_e32 v10, 1, v0
	v_lshlrev_b32_e32 v0, 30, v0
	v_cmp_eq_u32_e64 s[6:7], 0, v10
	v_and_b32_e32 v0, 0x80000000, v0
	v_xor_b32_e32 v5, v5, v4
	v_cndmask_b32_e64 v8, v9, v8, s[6:7]
	v_xor_b32_e32 v0, v5, v0
	v_xor_b32_e32 v0, v0, v8
	v_cmp_class_f32_e64 s[6:7], v4, s42
	v_mul_f32_e32 v4, v30, v6
	v_and_b32_e32 v5, 0x7fffffff, v4
	v_cndmask_b32_e64 v0, v29, v0, s[6:7]
	v_cvt_pk_bf16_f32 v0, v0, s0
	v_cmp_nlt_f32_e64 s[6:7], |v4|, s3
	global_store_short v[2:3], v0, off offset:80
	s_and_saveexec_b64 s[8:9], s[6:7]
	s_xor_b64 s[20:21], exec, s[8:9]
	s_cbranch_execz .LBB0_277
	v_lshrrev_b32_e32 v0, 23, v5
	v_add_u32_e32 v0, 0xffffff88, v0
	v_cmp_lt_u32_e64 s[6:7], 63, v0
	s_nop 1
	v_cndmask_b32_e64 v6, 0, v25, s[6:7]
	v_add_u32_e32 v0, v6, v0
	v_cmp_lt_u32_e64 s[8:9], 31, v0
	s_nop 1
	v_cndmask_b32_e64 v6, 0, v26, s[8:9]
	v_add_u32_e32 v0, v6, v0
	v_cmp_lt_u32_e64 s[10:11], 31, v0
	s_nop 1
	v_cndmask_b32_e64 v6, 0, v26, s[10:11]
	v_add_u32_e32 v6, v6, v0
	v_and_b32_e32 v0, 0x7fffff, v5
	v_or_b32_e32 v31, 0x800000, v0
	v_mad_u64_u32 v[8:9], s[12:13], v31, s30, 0
	v_mov_b32_e32 v0, v9
	v_mad_u64_u32 v[10:11], s[12:13], v31, s31, v[0:1]
	v_mov_b32_e32 v0, v11
	v_mad_u64_u32 v[12:13], s[12:13], v31, s33, v[0:1]
	v_mov_b32_e32 v0, v13
	v_mad_u64_u32 v[14:15], s[12:13], v31, s34, v[0:1]
	v_mov_b32_e32 v0, v15
	v_mad_u64_u32 v[18:19], s[12:13], v31, s35, v[0:1]
	v_mov_b32_e32 v0, v19
	v_mad_u64_u32 v[20:21], s[12:13], v31, s36, v[0:1]
	v_mov_b32_e32 v0, v21
	v_mad_u64_u32 v[32:33], s[12:13], v31, s37, v[0:1]
	v_cndmask_b32_e64 v9, v20, v14, s[6:7]
	v_cndmask_b32_e64 v0, v32, v18, s[6:7]
	v_cndmask_b32_e64 v13, v33, v20, s[6:7]
	v_cndmask_b32_e64 v11, v0, v9, s[8:9]
	v_cndmask_b32_e64 v0, v13, v0, s[8:9]
	v_cndmask_b32_e64 v13, v18, v12, s[6:7]
	v_cndmask_b32_e64 v9, v9, v13, s[8:9]
	v_sub_u32_e32 v15, 32, v6
	v_cmp_eq_u32_e64 s[12:13], 0, v6
	v_cndmask_b32_e64 v6, v14, v10, s[6:7]
	v_cndmask_b32_e64 v0, v0, v11, s[10:11]
	v_cndmask_b32_e64 v11, v11, v9, s[10:11]
	v_cndmask_b32_e64 v10, v13, v6, s[8:9]
	v_alignbit_b32 v18, v0, v11, v15
	v_cndmask_b32_e64 v9, v9, v10, s[10:11]
	v_cndmask_b32_e64 v0, v18, v0, s[12:13]
	v_alignbit_b32 v13, v11, v9, v15
	v_cndmask_b32_e64 v8, v12, v8, s[6:7]
	v_cndmask_b32_e64 v11, v13, v11, s[12:13]
	v_bfe_u32 v18, v0, 29, 1
	v_cndmask_b32_e64 v6, v6, v8, s[8:9]
	v_alignbit_b32 v13, v0, v11, 30
	v_sub_u32_e32 v19, 0, v18
	v_cndmask_b32_e64 v6, v10, v6, s[10:11]
	v_xor_b32_e32 v13, v13, v19
	v_alignbit_b32 v8, v9, v6, v15
	v_cndmask_b32_e64 v8, v8, v9, s[12:13]
	v_ffbh_u32_e32 v10, v13
	v_alignbit_b32 v9, v11, v8, 30
	v_min_u32_e32 v10, 32, v10
	v_alignbit_b32 v6, v8, v6, 30
	v_xor_b32_e32 v9, v9, v19
	v_sub_u32_e32 v11, 31, v10
	v_xor_b32_e32 v6, v6, v19
	v_alignbit_b32 v12, v13, v9, v11
	v_alignbit_b32 v6, v9, v6, v11
	v_alignbit_b32 v8, v12, v6, 9
	v_ffbh_u32_e32 v9, v8
	v_min_u32_e32 v9, 32, v9
	v_lshrrev_b32_e32 v14, 29, v0
	v_not_b32_e32 v11, v9
	v_alignbit_b32 v6, v8, v6, v11
	v_lshlrev_b32_e32 v8, 31, v14
	v_or_b32_e32 v11, 0x33000000, v8
	v_add_lshl_u32 v9, v9, v10, 23
	v_lshrrev_b32_e32 v6, 9, v6
	v_sub_u32_e32 v9, v11, v9
	v_or_b32_e32 v8, 0.5, v8
	v_lshlrev_b32_e32 v10, 23, v10
	v_or_b32_e32 v6, v9, v6
	v_lshrrev_b32_e32 v9, 9, v12
	v_sub_u32_e32 v8, v8, v10
	v_or_b32_e32 v8, v9, v8
	v_mul_f32_e32 v9, 0x3fc90fda, v8
	v_fma_f32 v10, v8, s38, -v9
	v_fmac_f32_e32 v10, 0x33a22168, v8
	v_fmac_f32_e32 v10, 0x3fc90fda, v6
	v_lshrrev_b32_e32 v0, 30, v0
	v_add_f32_e32 v6, v9, v10
	v_add_u32_e32 v0, v18, v0
.LBB0_277:
	s_andn2_saveexec_b64 s[6:7], s[20:21]
	v_mul_f32_e64 v0, |v4|, s39
	v_rndne_f32_e32 v8, v0
	v_cvt_i32_f32_e32 v0, v8
	v_fma_f32 v6, v8, s40, |v4|
	v_fmac_f32_e32 v6, 0xb3a22168, v8
	v_fmac_f32_e32 v6, 0xa7c234c4, v8
	s_or_b64 exec, exec, s[6:7]
	v_mul_f32_e32 v8, v6, v6
	v_fmamk_f32 v9, v8, 0xb94c1982, v23
	v_fmaak_f32 v9, v8, v9, 0xbe2aaa9d
	v_mul_f32_e32 v9, v8, v9
	v_fmac_f32_e32 v6, v6, v9
	v_fmamk_f32 v9, v8, 0x37d75334, v24
	v_fmaak_f32 v9, v8, v9, 0x3d2aabf7
	v_fmaak_f32 v9, v8, v9, 0xbf000004
	v_fma_f32 v8, v8, v9, 1.0
	v_and_b32_e32 v9, 1, v0
	v_lshlrev_b32_e32 v0, 30, v0
	v_cmp_eq_u32_e64 s[6:7], 0, v9
	v_and_b32_e32 v0, 0x80000000, v0
	v_xor_b32_e32 v5, v5, v4
	v_cndmask_b32_e64 v6, v8, v6, s[6:7]
	v_xor_b32_e32 v0, v5, v0
	v_xor_b32_e32 v0, v0, v6
	v_cmp_class_f32_e64 s[6:7], v4, s42
	v_mul_f32_e32 v4, v30, v7
	v_and_b32_e32 v5, 0x7fffffff, v4
	v_cndmask_b32_e64 v0, v29, v0, s[6:7]
	v_cvt_pk_bf16_f32 v0, v0, s0
	v_cmp_nlt_f32_e64 s[6:7], |v4|, s3
	global_store_short v[2:3], v0, off offset:96
	s_and_saveexec_b64 s[8:9], s[6:7]
	s_xor_b64 s[20:21], exec, s[8:9]
	s_cbranch_execz .LBB0_281
	v_lshrrev_b32_e32 v0, 23, v5
	v_add_u32_e32 v0, 0xffffff88, v0
	v_cmp_lt_u32_e64 s[6:7], 63, v0
	s_nop 1
	v_cndmask_b32_e64 v6, 0, v25, s[6:7]
	v_add_u32_e32 v0, v6, v0
	v_cmp_lt_u32_e64 s[8:9], 31, v0
	s_nop 1
	v_cndmask_b32_e64 v6, 0, v26, s[8:9]
	v_add_u32_e32 v0, v6, v0
	v_cmp_lt_u32_e64 s[10:11], 31, v0
	s_nop 1
	v_cndmask_b32_e64 v6, 0, v26, s[10:11]
	v_add_u32_e32 v30, v6, v0
	v_and_b32_e32 v0, 0x7fffff, v5
	v_or_b32_e32 v20, 0x800000, v0
	v_mad_u64_u32 v[6:7], s[12:13], v20, s30, 0
	v_mov_b32_e32 v0, v7
	v_mad_u64_u32 v[8:9], s[12:13], v20, s31, v[0:1]
	v_mov_b32_e32 v0, v9
	v_mad_u64_u32 v[10:11], s[12:13], v20, s33, v[0:1]
	v_mov_b32_e32 v0, v11
	v_mad_u64_u32 v[12:13], s[12:13], v20, s34, v[0:1]
	v_mov_b32_e32 v0, v13
	v_mad_u64_u32 v[14:15], s[12:13], v20, s35, v[0:1]
	v_mov_b32_e32 v0, v15
	v_mad_u64_u32 v[18:19], s[12:13], v20, s36, v[0:1]
	v_mov_b32_e32 v0, v19
	v_mad_u64_u32 v[20:21], s[12:13], v20, s37, v[0:1]
	v_cndmask_b32_e64 v7, v18, v12, s[6:7]
	v_cndmask_b32_e64 v0, v20, v14, s[6:7]
	v_cndmask_b32_e64 v11, v21, v18, s[6:7]
	v_cndmask_b32_e64 v9, v0, v7, s[8:9]
	v_cndmask_b32_e64 v0, v11, v0, s[8:9]
	v_cndmask_b32_e64 v11, v14, v10, s[6:7]
	v_cndmask_b32_e64 v7, v7, v11, s[8:9]
	v_cndmask_b32_e64 v8, v12, v8, s[6:7]
	v_cndmask_b32_e64 v0, v0, v9, s[10:11]
	v_cndmask_b32_e64 v9, v9, v7, s[10:11]
	v_sub_u32_e32 v13, 32, v30
	v_cndmask_b32_e64 v11, v11, v8, s[8:9]
	v_alignbit_b32 v14, v0, v9, v13
	v_cmp_eq_u32_e64 s[12:13], 0, v30
	v_cndmask_b32_e64 v7, v7, v11, s[10:11]
	v_cndmask_b32_e64 v6, v10, v6, s[6:7]
	v_cndmask_b32_e64 v0, v14, v0, s[12:13]
	v_alignbit_b32 v12, v9, v7, v13
	v_cndmask_b32_e64 v6, v8, v6, s[8:9]
	v_cndmask_b32_e64 v9, v12, v9, s[12:13]
	v_bfe_u32 v15, v0, 29, 1
	v_cndmask_b32_e64 v6, v11, v6, s[10:11]
	v_alignbit_b32 v12, v0, v9, 30
	v_sub_u32_e32 v18, 0, v15
	v_alignbit_b32 v8, v7, v6, v13
	v_xor_b32_e32 v12, v12, v18
	v_cndmask_b32_e64 v7, v8, v7, s[12:13]
	v_alignbit_b32 v8, v9, v7, 30
	v_ffbh_u32_e32 v9, v12
	v_min_u32_e32 v9, 32, v9
	v_alignbit_b32 v6, v7, v6, 30
	v_xor_b32_e32 v8, v8, v18
	v_sub_u32_e32 v10, 31, v9
	v_xor_b32_e32 v6, v6, v18
	v_alignbit_b32 v11, v12, v8, v10
	v_alignbit_b32 v6, v8, v6, v10
	v_alignbit_b32 v7, v11, v6, 9
	v_ffbh_u32_e32 v8, v7
	v_min_u32_e32 v8, 32, v8
	v_lshrrev_b32_e32 v14, 29, v0
	v_not_b32_e32 v10, v8
	v_alignbit_b32 v6, v7, v6, v10
	v_lshlrev_b32_e32 v7, 31, v14
	v_or_b32_e32 v10, 0x33000000, v7
	v_add_lshl_u32 v8, v8, v9, 23
	v_lshrrev_b32_e32 v6, 9, v6
	v_sub_u32_e32 v8, v10, v8
	v_or_b32_e32 v7, 0.5, v7
	v_lshlrev_b32_e32 v9, 23, v9
	v_or_b32_e32 v6, v8, v6
	v_lshrrev_b32_e32 v8, 9, v11
	v_sub_u32_e32 v7, v7, v9
	v_or_b32_e32 v7, v8, v7
	v_mul_f32_e32 v8, 0x3fc90fda, v7
	v_fma_f32 v9, v7, s38, -v8
	v_fmac_f32_e32 v9, 0x33a22168, v7
	v_fmac_f32_e32 v9, 0x3fc90fda, v6
	v_lshrrev_b32_e32 v0, 30, v0
	v_add_f32_e32 v6, v8, v9
	v_add_u32_e32 v0, v15, v0

.LBB0_518:
	s_ashr_i32 s0, s5, 8
	v_readlane_b32 s1, v252, 47
	s_add_i32 s4, s1, s0
	v_readlane_b32 s0, v252, 40
	v_readlane_b32 s1, v252, 41
	v_mov_b32_e32 v146, v162
	s_and_b64 s[0:1], s[0:1], exec
	v_writelane_b32 v252, s5, 56
	s_cselect_b32 s68, s4, s5
	v_mov_b32_e32 v32, v146
	s_barrier
	v_readlane_b32 s4, v252, 22
	v_lshlrev_b32_e32 v2, 11, v32
	v_and_b32_e32 v144, 0x1000, v2
	v_readlane_b32 s6, v252, 24
	v_readlane_b32 s7, v252, 25
	v_bfe_u32 v33, v32, 5, 1
	s_ashr_i32 s69, s68, 31
	v_lshl_add_u64 v[0:1], s[6:7], 0, v[144:145]
	v_and_b32_e32 v144, 0x800, v2
	v_lshl_add_u64 v[0:1], v[0:1], 0, v[144:145]
	v_lshl_add_u64 v[0:1], s[68:69], 2, v[0:1]
	v_lshlrev_b32_e32 v144, 16, v33
	v_lshl_add_u64 v[0:1], v[0:1], 0, v[144:145]
	v_add_co_u32_e32 v2, vcc, s71, v0
	s_movk_i32 s0, 0x4000
	s_nop 0
	v_addc_co_u32_e32 v3, vcc, 0, v1, vcc
	v_add_co_u32_e32 v4, vcc, s0, v0
	s_movk_i32 s0, 0x6000
	s_nop 0
	v_addc_co_u32_e32 v5, vcc, 0, v1, vcc
	v_add_co_u32_e32 v6, vcc, s0, v0
	s_mov_b32 s0, 0x8000
	s_nop 0
	v_addc_co_u32_e32 v7, vcc, 0, v1, vcc
	v_add_co_u32_e32 v8, vcc, s0, v0
	s_mov_b32 s0, 0xa000
	s_nop 0
	v_addc_co_u32_e32 v9, vcc, 0, v1, vcc
	v_add_co_u32_e32 v10, vcc, s0, v0
	s_mov_b32 s0, 0xc000
	s_nop 0
	v_addc_co_u32_e32 v11, vcc, 0, v1, vcc
	v_add_co_u32_e32 v12, vcc, s0, v0
	s_mov_b32 s0, 0xe000
	s_nop 0
	v_addc_co_u32_e32 v13, vcc, 0, v1, vcc
	v_add_co_u32_e32 v14, vcc, s0, v0
	s_mov_b32 s0, 0x20000
	s_nop 0
	v_addc_co_u32_e32 v15, vcc, 0, v1, vcc
	global_load_dword v19, v[0:1], off
	global_load_dword v20, v[2:3], off
	global_load_dword v21, v[4:5], off
	global_load_dword v22, v[6:7], off
	global_load_dword v23, v[8:9], off
	global_load_dword v24, v[10:11], off
	global_load_dword v25, v[12:13], off
	global_load_dword v26, v[14:15], off
	v_add_co_u32_e32 v2, vcc, s0, v0
	s_mov_b32 s0, 0x22000
	s_nop 0
	v_addc_co_u32_e32 v3, vcc, 0, v1, vcc
	v_add_co_u32_e32 v4, vcc, s0, v0
	s_mov_b32 s0, 0x24000
	s_nop 0
	v_addc_co_u32_e32 v5, vcc, 0, v1, vcc
	v_add_co_u32_e32 v6, vcc, s0, v0
	s_mov_b32 s0, 0x26000
	s_nop 0
	v_addc_co_u32_e32 v7, vcc, 0, v1, vcc
	v_add_co_u32_e32 v8, vcc, s0, v0
	s_mov_b32 s0, 0x28000
	s_nop 0
	v_addc_co_u32_e32 v9, vcc, 0, v1, vcc
	v_add_co_u32_e32 v10, vcc, s0, v0
	s_mov_b32 s0, 0x2a000
	s_nop 0
	v_addc_co_u32_e32 v11, vcc, 0, v1, vcc
	v_add_co_u32_e32 v12, vcc, s0, v0
	s_mov_b32 s0, 0x2c000
	s_nop 0
	v_addc_co_u32_e32 v13, vcc, 0, v1, vcc
	v_add_co_u32_e32 v14, vcc, s0, v0
	s_mov_b32 s0, 0x2e000
	s_nop 0
	v_addc_co_u32_e32 v15, vcc, 0, v1, vcc
	v_add_co_u32_e32 v16, vcc, s0, v0
	s_mov_b32 s0, 0x40000
	s_nop 0
	v_addc_co_u32_e32 v17, vcc, 0, v1, vcc
	global_load_dword v27, v[2:3], off
	global_load_dword v28, v[4:5], off
	global_load_dword v29, v[6:7], off
	global_load_dword v30, v[8:9], off
	global_load_dword v31, v[10:11], off
	global_load_dword v34, v[12:13], off
	global_load_dword v35, v[14:15], off
	global_load_dword v36, v[16:17], off
	v_add_co_u32_e32 v2, vcc, s0, v0
	s_mov_b32 s0, 0x42000
	s_nop 0
	v_addc_co_u32_e32 v3, vcc, 0, v1, vcc
	v_add_co_u32_e32 v4, vcc, s0, v0
	s_mov_b32 s0, 0x44000
	s_nop 0
	v_addc_co_u32_e32 v5, vcc, 0, v1, vcc
	v_add_co_u32_e32 v6, vcc, s0, v0
	s_mov_b32 s0, 0x46000
	s_nop 0
	v_addc_co_u32_e32 v7, vcc, 0, v1, vcc
	v_add_co_u32_e32 v8, vcc, s0, v0
	s_mov_b32 s0, 0x48000
	s_nop 0
	v_addc_co_u32_e32 v9, vcc, 0, v1, vcc
	v_add_co_u32_e32 v10, vcc, s0, v0
	s_mov_b32 s0, 0x4a000
	s_nop 0
	v_addc_co_u32_e32 v11, vcc, 0, v1, vcc
	v_add_co_u32_e32 v12, vcc, s0, v0
	s_mov_b32 s0, 0x4c000
	s_nop 0
	v_addc_co_u32_e32 v13, vcc, 0, v1, vcc
	v_add_co_u32_e32 v14, vcc, s0, v0
	s_mov_b32 s0, 0x4e000
	s_nop 0
	v_addc_co_u32_e32 v15, vcc, 0, v1, vcc
	v_add_co_u32_e32 v16, vcc, s0, v0
	s_mov_b32 s0, 0x60000
	s_nop 0
	v_addc_co_u32_e32 v17, vcc, 0, v1, vcc
	global_load_dword v37, v[2:3], off
	global_load_dword v38, v[4:5], off
	global_load_dword v39, v[6:7], off
	global_load_dword v40, v[8:9], off
	global_load_dword v41, v[10:11], off
	global_load_dword v42, v[12:13], off
	global_load_dword v43, v[14:15], off
	global_load_dword v44, v[16:17], off
	v_add_co_u32_e32 v2, vcc, s0, v0
	s_mov_b32 s0, 0x62000
	s_nop 0
	v_addc_co_u32_e32 v3, vcc, 0, v1, vcc
	v_add_co_u32_e32 v4, vcc, s0, v0
	s_mov_b32 s0, 0x64000
	s_nop 0
	v_addc_co_u32_e32 v5, vcc, 0, v1, vcc
	v_add_co_u32_e32 v6, vcc, s0, v0
	s_mov_b32 s0, 0x66000
	s_nop 0
	v_addc_co_u32_e32 v7, vcc, 0, v1, vcc
	v_add_co_u32_e32 v8, vcc, s0, v0
	s_mov_b32 s0, 0x68000
	s_nop 0
	v_addc_co_u32_e32 v9, vcc, 0, v1, vcc
	v_add_co_u32_e32 v10, vcc, s0, v0
	s_mov_b32 s0, 0x6a000
	s_nop 0
	v_addc_co_u32_e32 v11, vcc, 0, v1, vcc
	v_add_co_u32_e32 v12, vcc, s0, v0
	s_mov_b32 s0, 0x6c000
	s_nop 0
	v_addc_co_u32_e32 v13, vcc, 0, v1, vcc
	v_add_co_u32_e32 v14, vcc, s0, v0
	s_mov_b32 s0, 0x6e000
	s_nop 0
	v_addc_co_u32_e32 v15, vcc, 0, v1, vcc
	v_add_co_u32_e32 v0, vcc, s0, v0
	v_cvt_f32_i32_e32 v18, s68
	s_nop 0
	v_addc_co_u32_e32 v1, vcc, 0, v1, vcc
	global_load_dword v2, v[2:3], off
	s_nop 0
	global_load_dword v3, v[4:5], off
	s_nop 0
	global_load_dword v4, v[6:7], off
	global_load_dword v5, v[8:9], off
	s_nop 0
	global_load_dword v6, v[10:11], off
	global_load_dword v7, v[12:13], off
	global_load_dword v8, v[14:15], off
	s_nop 0
	global_load_dword v0, v[0:1], off
	s_mov_b32 s4, 0x43ff8000
	v_div_scale_f32 v1, s[0:1], s4, s4, v18
	v_rcp_f32_e32 v9, v1
	s_sub_i32 s0, 0x1ff, s68
	v_cvt_f32_i32_e32 v13, s0
	v_readlane_b32 s5, v252, 23
	v_fma_f32 v10, -v1, v9, 1.0
	v_fmac_f32_e32 v9, v10, v9
	v_div_scale_f32 v10, vcc, v18, s4, v18
	v_mul_f32_e32 v11, v10, v9
	v_fma_f32 v12, -v1, v11, v10
	v_fmac_f32_e32 v11, v12, v9
	v_fma_f32 v1, -v1, v11, v10
	v_div_scale_f32 v10, s[0:1], s4, s4, v13
	v_rcp_f32_e32 v12, v10
	v_div_fmas_f32 v1, v1, v9, v11
	v_div_fixup_f32 v1, v1, s4, v18
	v_fmamk_f32 v144, v1, 0xc1447cbd, v152
	v_fma_f32 v1, -v10, v12, 1.0
	v_fmac_f32_e32 v12, v1, v12
	v_div_scale_f32 v1, vcc, v13, s4, v13
	v_mul_f32_e32 v9, v1, v12
	v_fma_f32 v11, -v10, v9, v1
	v_fmac_f32_e32 v9, v11, v12
	v_fma_f32 v1, -v10, v9, v1
	v_div_fmas_f32 v1, v1, v12, v9
	v_and_b32_e32 v9, 31, v32
	v_div_fixup_f32 v1, v1, s4, v13
	v_cmp_gt_u32_e32 vcc, 4, v9
	v_fmamk_f32 v147, v1, 0xc1447cbd, v152
	v_cmp_eq_u32_e64 s[0:1], 0, v33
	s_waitcnt vmcnt(31)
	v_cndmask_b32_e32 v1, 0, v19, vcc
	s_waitcnt vmcnt(30)
	v_cndmask_b32_e32 v10, 0, v20, vcc
	v_cvt_pk_bf16_f32 v16, v1, v10
	s_waitcnt vmcnt(23)
	v_cndmask_b32_e32 v1, 0, v27, vcc
	s_waitcnt vmcnt(22)
	v_cndmask_b32_e32 v10, 0, v28, vcc
	v_cvt_pk_bf16_f32 v20, v1, v10
	s_waitcnt vmcnt(15)
	v_cndmask_b32_e32 v1, 0, v37, vcc
	s_waitcnt vmcnt(14)
	v_cndmask_b32_e32 v10, 0, v38, vcc
	v_cndmask_b32_e32 v13, 0, v23, vcc
	v_cndmask_b32_e32 v14, 0, v24, vcc
	v_cvt_pk_bf16_f32 v24, v1, v10
	v_cvt_pk_bf16_f32 v18, v13, v14
	v_cndmask_b32_e32 v13, 0, v31, vcc
	v_cndmask_b32_e32 v11, 0, v21, vcc
	v_cndmask_b32_e32 v12, 0, v22, vcc
	v_cndmask_b32_e32 v15, 0, v25, vcc
	v_cndmask_b32_e32 v19, 0, v26, vcc
	v_cvt_pk_bf16_f32 v17, v11, v12
	v_cvt_pk_bf16_f32 v19, v15, v19
	v_cndmask_b32_e32 v11, 0, v29, vcc
	v_cndmask_b32_e32 v12, 0, v30, vcc
	v_cndmask_b32_e32 v14, 0, v34, vcc
	v_cndmask_b32_e32 v15, 0, v35, vcc
	v_cndmask_b32_e32 v23, 0, v36, vcc
	v_cvt_pk_bf16_f32 v21, v11, v12
	v_cvt_pk_bf16_f32 v22, v13, v14
	v_cvt_pk_bf16_f32 v23, v15, v23
	s_waitcnt vmcnt(13)
	v_cndmask_b32_e32 v11, 0, v39, vcc
	s_waitcnt vmcnt(12)
	v_cndmask_b32_e32 v12, 0, v40, vcc
	s_waitcnt vmcnt(11)
	v_cndmask_b32_e32 v13, 0, v41, vcc
	s_waitcnt vmcnt(10)
	v_cndmask_b32_e32 v14, 0, v42, vcc
	s_waitcnt vmcnt(9)
	v_cndmask_b32_e32 v15, 0, v43, vcc
	s_waitcnt vmcnt(8)
	v_cndmask_b32_e32 v27, 0, v44, vcc
	v_cvt_pk_bf16_f32 v25, v11, v12
	v_cvt_pk_bf16_f32 v26, v13, v14
	v_cvt_pk_bf16_f32 v27, v15, v27
	s_mov_b64 s[4:5], 0
	s_waitcnt vmcnt(7)
	v_cndmask_b32_e32 v1, 0, v2, vcc
	s_waitcnt vmcnt(6)
	v_cndmask_b32_e32 v2, 0, v3, vcc
	s_waitcnt vmcnt(5)
	v_cndmask_b32_e32 v3, 0, v4, vcc
	s_waitcnt vmcnt(4)
	v_cndmask_b32_e32 v4, 0, v5, vcc
	s_waitcnt vmcnt(3)
	v_cndmask_b32_e32 v5, 0, v6, vcc
	s_waitcnt vmcnt(2)
	v_cndmask_b32_e32 v6, 0, v7, vcc
	s_waitcnt vmcnt(1)
	v_cndmask_b32_e32 v7, 0, v8, vcc
	s_waitcnt vmcnt(0)
	v_cndmask_b32_e32 v0, 0, v0, vcc
	v_cvt_pk_bf16_f32 v31, v7, v0
	v_lshlrev_b32_e32 v0, 4, v32
	v_and_b32_e32 v0, 0xfffffc00, v0
	v_cvt_pk_bf16_f32 v28, v1, v2
	v_ashrrev_i32_e32 v149, 31, v0
	v_or_b32_e32 v148, v0, v9
	v_lshlrev_b32_e32 v2, 6, v32
	v_lshlrev_b64 v[0:1], 7, v[148:149]
	v_and_b32_e32 v2, 0xfffff000, v2
	v_lshl_or_b32 v149, v9, 2, v2
	v_lshl_or_b32 v0, v33, 4, v0
	v_cvt_pk_bf16_f32 v29, v3, v4
	v_cvt_pk_bf16_f32 v30, v5, v6
	v_sub_u32_e32 v155, 0, v149
	v_sub_u32_e32 v0, v148, v9
	v_lshlrev_b32_e32 v0, 7, v0
	v_lshl_add_u32 v0, v9, 4, v0
	v_lshl_add_u32 v0, v33, 9, v0
	v_mov_b32_e32 v1, 0
	v_lshl_add_u64 v[150:151], s[86:87], 0, v[0:1]
	v_readlane_b32 s8, v252, 26
	v_readlane_b32 s9, v252, 27
	v_readlane_b32 s10, v252, 28
	v_readlane_b32 s11, v252, 29
	v_readlane_b32 s12, v252, 30
	v_readlane_b32 s13, v252, 31
	v_readlane_b32 s14, v252, 32
	v_readlane_b32 s15, v252, 33
	v_readlane_b32 s16, v252, 34
	v_readlane_b32 s17, v252, 35
	v_readlane_b32 s18, v252, 36
	v_readlane_b32 s19, v252, 37
	s_branch .LBB0_520

.LBB0_520:
	v_lshl_add_u64 v[36:37], v[150:151], 0, s[4:5]
	s_nop 0
	v_add_co_u32_e32 v4, vcc, 0xe200000, v36
	s_nop 1
	v_addc_co_u32_e32 v5, vcc, 0, v37, vcc
	global_load_dwordx4 v[0:3], v[4:5], off
	global_load_dwordx4 v[32:35], v[4:5], off offset:1024
	global_load_dwordx4 v[40:43], v[4:5], off offset:2048
	v_add_co_u32_e32 v6, vcc, 0xe201000, v36
	global_load_dwordx4 v[156:159], v[4:5], off offset:3072
	s_nop 0
	v_addc_co_u32_e32 v7, vcc, 0, v37, vcc
	v_add_co_u32_e32 v4, vcc, 0xe202000, v36
	global_load_dwordx4 v[140:143], v[6:7], off
	global_load_dwordx4 v[136:139], v[6:7], off offset:1024
	global_load_dwordx4 v[132:135], v[6:7], off offset:2048
	global_load_dwordx4 v[128:131], v[6:7], off offset:3072
	v_addc_co_u32_e32 v5, vcc, 0, v37, vcc
	v_add_co_u32_e32 v6, vcc, 0xe203000, v36
	global_load_dwordx4 v[124:127], v[4:5], off
	global_load_dwordx4 v[120:123], v[4:5], off offset:1024
	global_load_dwordx4 v[116:119], v[4:5], off offset:2048
	global_load_dwordx4 v[112:115], v[4:5], off offset:3072
	v_addc_co_u32_e32 v7, vcc, 0, v37, vcc
	v_add_co_u32_e32 v4, vcc, 0xe204000, v36
	global_load_dwordx4 v[108:111], v[6:7], off
	global_load_dwordx4 v[104:107], v[6:7], off offset:1024
	global_load_dwordx4 v[100:103], v[6:7], off offset:2048
	global_load_dwordx4 v[96:99], v[6:7], off offset:3072
	v_addc_co_u32_e32 v5, vcc, 0, v37, vcc
	v_add_co_u32_e32 v6, vcc, 0xe205000, v36
	global_load_dwordx4 v[92:95], v[4:5], off
	global_load_dwordx4 v[88:91], v[4:5], off offset:1024
	global_load_dwordx4 v[84:87], v[4:5], off offset:2048
	global_load_dwordx4 v[80:83], v[4:5], off offset:3072
	v_addc_co_u32_e32 v7, vcc, 0, v37, vcc
	global_load_dwordx4 v[76:79], v[6:7], off
	global_load_dwordx4 v[68:71], v[6:7], off offset:1024
	global_load_dwordx4 v[56:59], v[6:7], off offset:2048
	global_load_dwordx4 v[48:51], v[6:7], off offset:3072
	v_add_co_u32_e32 v38, vcc, 0xe206000, v36
	s_waitcnt vmcnt(23)
	v_mfma_f32_32x32x16_bf16 v[0:15], v[16:19], v[0:3], 0
	v_addc_co_u32_e32 v39, vcc, 0, v37, vcc
	v_add_co_u32_e32 v44, vcc, 0xe207000, v36
	global_load_dwordx4 v[72:75], v[38:39], off
	global_load_dwordx4 v[60:63], v[38:39], off offset:1024
	v_addc_co_u32_e32 v45, vcc, 0, v37, vcc
	s_waitcnt vmcnt(24)
	v_mfma_f32_32x32x16_bf16 v[0:15], v[20:23], v[32:35], v[0:15]
	global_load_dwordx4 v[64:67], v[38:39], off offset:2048
	global_load_dwordx4 v[52:55], v[38:39], off offset:3072
	s_nop 0
	global_load_dwordx4 v[36:39], v[44:45], off
	global_load_dwordx4 v[32:35], v[44:45], off offset:1024
	s_waitcnt vmcnt(27)
	v_mfma_f32_32x32x16_bf16 v[0:15], v[24:27], v[40:43], v[0:15]
	global_load_dwordx4 v[40:43], v[44:45], off offset:2048
	s_nop 0
	global_load_dwordx4 v[44:47], v[44:45], off offset:3072
	s_waitcnt vmcnt(28)
	v_mfma_f32_32x32x16_bf16 v[0:15], v[28:31], v[156:159], v[0:15]
	v_add_u32_e32 v157, 16, v149
	v_add_u32_e32 v156, 16, v155
	s_and_saveexec_b64 s[6:7], s[0:1]
	s_cbranch_execz .LBB0_522
	s_nop 7
	v_cvt_f32_i32_e32 v4, v148
	v_mul_f32_e32 v4, 0xb9000400, v4
	v_mul_f32_e64 v5, |v144|, v4
	v_mul_f32_e64 v4, |v147|, v4
	v_mul_f32_e32 v5, 0x3fb8aa3b, v5
	v_mul_f32_e32 v4, 0x3fb8aa3b, v4
	v_exp_f32_e32 v5, v5
	v_exp_f32_e32 v4, v4
	v_mul_f32_e32 v0, v5, v0
	v_mul_f32_e32 v1, v4, v1
	v_mul_f32_e32 v2, v5, v2
	ds_write_b32 v157, v0
	ds_write_b32 v156, v1 offset:65532
	v_add_u32_e32 v0, 0x10000, v157
	ds_write_b32 v0, v2
	v_mul_f32_e32 v0, v4, v3
	v_add_u32_e32 v1, 0x1fffc, v156
	ds_write_b32 v1, v0

.LBB0_890:
	s_ashr_i32 s0, s29, 8
	v_readlane_b32 s1, v252, 56
	s_add_i32 s4, s1, s0
	v_readlane_b32 s0, v252, 40
	v_readlane_b32 s1, v252, 41
	v_mov_b32_e32 v146, v162
	s_and_b64 s[0:1], s[0:1], exec
	s_cselect_b32 s62, s4, s29
	v_mov_b32_e32 v32, v146
	s_barrier
	v_readlane_b32 s4, v252, 22
	v_lshlrev_b32_e32 v2, 11, v32
	v_and_b32_e32 v144, 0x1000, v2
	v_readlane_b32 s6, v252, 24
	v_readlane_b32 s7, v252, 25
	v_bfe_u32 v33, v32, 5, 1
	s_ashr_i32 s63, s62, 31
	v_lshl_add_u64 v[0:1], s[6:7], 0, v[144:145]
	v_and_b32_e32 v144, 0x800, v2
	v_lshl_add_u64 v[0:1], v[0:1], 0, v[144:145]
	v_lshl_add_u64 v[0:1], s[62:63], 2, v[0:1]
	v_lshlrev_b32_e32 v144, 16, v33
	v_lshl_add_u64 v[0:1], v[0:1], 0, v[144:145]
	s_mov_b32 s0, 0x80000
	v_add_co_u32_e32 v2, vcc, s0, v0
	s_mov_b32 s0, 0x82000
	s_nop 0
	v_addc_co_u32_e32 v3, vcc, 0, v1, vcc
	v_add_co_u32_e32 v4, vcc, s0, v0
	s_mov_b32 s0, 0x84000
	s_nop 0
	v_addc_co_u32_e32 v5, vcc, 0, v1, vcc
	v_add_co_u32_e32 v6, vcc, s0, v0
	s_mov_b32 s0, 0x86000
	s_nop 0
	v_addc_co_u32_e32 v7, vcc, 0, v1, vcc
	v_add_co_u32_e32 v8, vcc, s0, v0
	s_mov_b32 s0, 0x88000
	s_nop 0
	v_addc_co_u32_e32 v9, vcc, 0, v1, vcc
	v_add_co_u32_e32 v10, vcc, s0, v0
	s_mov_b32 s0, 0x8a000
	s_nop 0
	v_addc_co_u32_e32 v11, vcc, 0, v1, vcc
	v_add_co_u32_e32 v12, vcc, s0, v0
	s_mov_b32 s0, 0x8c000
	s_nop 0
	v_addc_co_u32_e32 v13, vcc, 0, v1, vcc
	v_add_co_u32_e32 v14, vcc, s0, v0
	s_mov_b32 s0, 0x8e000
	s_nop 0
	v_addc_co_u32_e32 v15, vcc, 0, v1, vcc
	v_add_co_u32_e32 v16, vcc, s0, v0
	s_mov_b32 s0, 0xa0000
	s_nop 0
	v_addc_co_u32_e32 v17, vcc, 0, v1, vcc
	global_load_dword v19, v[2:3], off
	global_load_dword v20, v[4:5], off
	global_load_dword v21, v[6:7], off
	global_load_dword v22, v[8:9], off
	global_load_dword v23, v[10:11], off
	global_load_dword v24, v[12:13], off
	global_load_dword v25, v[14:15], off
	global_load_dword v26, v[16:17], off
	v_add_co_u32_e32 v2, vcc, s0, v0
	s_mov_b32 s0, 0xa2000
	s_nop 0
	v_addc_co_u32_e32 v3, vcc, 0, v1, vcc
	v_add_co_u32_e32 v4, vcc, s0, v0
	s_mov_b32 s0, 0xa4000
	s_nop 0
	v_addc_co_u32_e32 v5, vcc, 0, v1, vcc
	v_add_co_u32_e32 v6, vcc, s0, v0
	s_mov_b32 s0, 0xa6000
	s_nop 0
	v_addc_co_u32_e32 v7, vcc, 0, v1, vcc
	v_add_co_u32_e32 v8, vcc, s0, v0
	s_mov_b32 s0, 0xa8000
	s_nop 0
	v_addc_co_u32_e32 v9, vcc, 0, v1, vcc
	v_add_co_u32_e32 v10, vcc, s0, v0
	s_mov_b32 s0, 0xaa000
	s_nop 0
	v_addc_co_u32_e32 v11, vcc, 0, v1, vcc
	v_add_co_u32_e32 v12, vcc, s0, v0
	s_mov_b32 s0, 0xac000
	s_nop 0
	v_addc_co_u32_e32 v13, vcc, 0, v1, vcc
	v_add_co_u32_e32 v14, vcc, s0, v0
	s_mov_b32 s0, 0xae000
	s_nop 0
	v_addc_co_u32_e32 v15, vcc, 0, v1, vcc
	v_add_co_u32_e32 v16, vcc, s0, v0
	s_mov_b32 s0, 0xc0000
	s_nop 0
	v_addc_co_u32_e32 v17, vcc, 0, v1, vcc
	global_load_dword v27, v[2:3], off
	global_load_dword v28, v[4:5], off
	global_load_dword v29, v[6:7], off
	global_load_dword v30, v[8:9], off
	global_load_dword v31, v[10:11], off
	global_load_dword v34, v[12:13], off
	global_load_dword v35, v[14:15], off
	global_load_dword v36, v[16:17], off
	v_add_co_u32_e32 v2, vcc, s0, v0
	s_mov_b32 s0, 0xc2000
	s_nop 0
	v_addc_co_u32_e32 v3, vcc, 0, v1, vcc
	v_add_co_u32_e32 v4, vcc, s0, v0
	s_mov_b32 s0, 0xc4000
	s_nop 0
	v_addc_co_u32_e32 v5, vcc, 0, v1, vcc
	v_add_co_u32_e32 v6, vcc, s0, v0
	s_mov_b32 s0, 0xc6000
	s_nop 0
	v_addc_co_u32_e32 v7, vcc, 0, v1, vcc
	v_add_co_u32_e32 v8, vcc, s0, v0
	s_mov_b32 s0, 0xc8000
	s_nop 0
	v_addc_co_u32_e32 v9, vcc, 0, v1, vcc
	v_add_co_u32_e32 v10, vcc, s0, v0
	s_mov_b32 s0, 0xca000
	s_nop 0
	v_addc_co_u32_e32 v11, vcc, 0, v1, vcc
	v_add_co_u32_e32 v12, vcc, s0, v0
	s_mov_b32 s0, 0xcc000
	s_nop 0
	v_addc_co_u32_e32 v13, vcc, 0, v1, vcc
	v_add_co_u32_e32 v14, vcc, s0, v0
	s_mov_b32 s0, 0xce000
	s_nop 0
	v_addc_co_u32_e32 v15, vcc, 0, v1, vcc
	v_add_co_u32_e32 v16, vcc, s0, v0
	s_mov_b32 s0, 0xe0000
	s_nop 0
	v_addc_co_u32_e32 v17, vcc, 0, v1, vcc
	global_load_dword v37, v[2:3], off
	global_load_dword v38, v[4:5], off
	global_load_dword v39, v[6:7], off
	global_load_dword v40, v[8:9], off
	global_load_dword v41, v[10:11], off
	global_load_dword v42, v[12:13], off
	global_load_dword v43, v[14:15], off
	global_load_dword v44, v[16:17], off
	v_add_co_u32_e32 v2, vcc, s0, v0
	s_mov_b32 s0, 0xe2000
	s_nop 0
	v_addc_co_u32_e32 v3, vcc, 0, v1, vcc
	v_add_co_u32_e32 v4, vcc, s0, v0
	s_mov_b32 s0, 0xe4000
	s_nop 0
	v_addc_co_u32_e32 v5, vcc, 0, v1, vcc
	v_add_co_u32_e32 v6, vcc, s0, v0
	s_mov_b32 s0, 0xe6000
	s_nop 0
	v_addc_co_u32_e32 v7, vcc, 0, v1, vcc
	v_add_co_u32_e32 v8, vcc, s0, v0
	s_mov_b32 s0, 0xe8000
	s_nop 0
	v_addc_co_u32_e32 v9, vcc, 0, v1, vcc
	v_add_co_u32_e32 v10, vcc, s0, v0
	s_mov_b32 s0, 0xea000
	s_nop 0
	v_addc_co_u32_e32 v11, vcc, 0, v1, vcc
	v_add_co_u32_e32 v12, vcc, s0, v0
	s_mov_b32 s0, 0xec000
	s_nop 0
	v_addc_co_u32_e32 v13, vcc, 0, v1, vcc
	v_add_co_u32_e32 v14, vcc, s0, v0
	s_mov_b32 s0, 0xee000
	s_nop 0
	v_addc_co_u32_e32 v15, vcc, 0, v1, vcc
	v_add_co_u32_e32 v0, vcc, s0, v0
	v_cvt_f32_i32_e32 v18, s62
	s_nop 0
	v_addc_co_u32_e32 v1, vcc, 0, v1, vcc
	global_load_dword v2, v[2:3], off
	s_nop 0
	global_load_dword v3, v[4:5], off
	s_nop 0
	global_load_dword v4, v[6:7], off
	global_load_dword v5, v[8:9], off
	s_nop 0
	global_load_dword v6, v[10:11], off
	global_load_dword v7, v[12:13], off
	global_load_dword v8, v[14:15], off
	s_nop 0
	global_load_dword v0, v[0:1], off
	s_mov_b32 s4, 0x43ff8000
	v_div_scale_f32 v1, s[0:1], s4, s4, v18
	v_rcp_f32_e32 v9, v1
	s_sub_i32 s0, 0x1ff, s62
	v_cvt_f32_i32_e32 v13, s0
	v_readlane_b32 s5, v252, 23
	v_fma_f32 v10, -v1, v9, 1.0
	v_fmac_f32_e32 v9, v10, v9
	v_div_scale_f32 v10, vcc, v18, s4, v18
	v_mul_f32_e32 v11, v10, v9
	v_fma_f32 v12, -v1, v11, v10
	v_fmac_f32_e32 v11, v12, v9
	v_fma_f32 v1, -v1, v11, v10
	v_div_scale_f32 v10, s[0:1], s4, s4, v13
	v_rcp_f32_e32 v12, v10
	v_div_fmas_f32 v1, v1, v9, v11
	v_div_fixup_f32 v1, v1, s4, v18
	v_fmamk_f32 v144, v1, 0xc1447cbd, v150
	v_fma_f32 v1, -v10, v12, 1.0
	v_fmac_f32_e32 v12, v1, v12
	v_div_scale_f32 v1, vcc, v13, s4, v13
	v_mul_f32_e32 v9, v1, v12
	v_fma_f32 v11, -v10, v9, v1
	v_fmac_f32_e32 v9, v11, v12
	v_fma_f32 v1, -v10, v9, v1
	v_div_fmas_f32 v1, v1, v12, v9
	v_and_b32_e32 v9, 31, v32
	v_div_fixup_f32 v1, v1, s4, v13
	v_cmp_gt_u32_e32 vcc, 4, v9
	v_fmamk_f32 v147, v1, 0xc1447cbd, v150
	v_cmp_eq_u32_e64 s[0:1], 0, v33
	s_waitcnt vmcnt(31)
	v_cndmask_b32_e32 v1, 0, v19, vcc
	s_waitcnt vmcnt(30)
	v_cndmask_b32_e32 v10, 0, v20, vcc
	v_cvt_pk_bf16_f32 v16, v1, v10
	s_waitcnt vmcnt(23)
	v_cndmask_b32_e32 v1, 0, v27, vcc
	s_waitcnt vmcnt(22)
	v_cndmask_b32_e32 v10, 0, v28, vcc
	v_cvt_pk_bf16_f32 v20, v1, v10
	s_waitcnt vmcnt(15)
	v_cndmask_b32_e32 v1, 0, v37, vcc
	s_waitcnt vmcnt(14)
	v_cndmask_b32_e32 v10, 0, v38, vcc
	v_cndmask_b32_e32 v13, 0, v23, vcc
	v_cndmask_b32_e32 v14, 0, v24, vcc
	v_cvt_pk_bf16_f32 v24, v1, v10
	v_cvt_pk_bf16_f32 v18, v13, v14
	v_cndmask_b32_e32 v13, 0, v31, vcc
	v_cndmask_b32_e32 v11, 0, v21, vcc
	v_cndmask_b32_e32 v12, 0, v22, vcc
	v_cndmask_b32_e32 v15, 0, v25, vcc
	v_cndmask_b32_e32 v19, 0, v26, vcc
	v_cvt_pk_bf16_f32 v17, v11, v12
	v_cvt_pk_bf16_f32 v19, v15, v19
	v_cndmask_b32_e32 v11, 0, v29, vcc
	v_cndmask_b32_e32 v12, 0, v30, vcc
	v_cndmask_b32_e32 v14, 0, v34, vcc
	v_cndmask_b32_e32 v15, 0, v35, vcc
	v_cndmask_b32_e32 v23, 0, v36, vcc
	v_cvt_pk_bf16_f32 v21, v11, v12
	v_cvt_pk_bf16_f32 v22, v13, v14
	v_cvt_pk_bf16_f32 v23, v15, v23
	s_waitcnt vmcnt(13)
	v_cndmask_b32_e32 v11, 0, v39, vcc
	s_waitcnt vmcnt(12)
	v_cndmask_b32_e32 v12, 0, v40, vcc
	s_waitcnt vmcnt(11)
	v_cndmask_b32_e32 v13, 0, v41, vcc
	s_waitcnt vmcnt(10)
	v_cndmask_b32_e32 v14, 0, v42, vcc
	s_waitcnt vmcnt(9)
	v_cndmask_b32_e32 v15, 0, v43, vcc
	s_waitcnt vmcnt(8)
	v_cndmask_b32_e32 v27, 0, v44, vcc
	v_cvt_pk_bf16_f32 v25, v11, v12
	v_cvt_pk_bf16_f32 v26, v13, v14
	v_cvt_pk_bf16_f32 v27, v15, v27
	s_mov_b64 s[4:5], 0
	s_waitcnt vmcnt(7)
	v_cndmask_b32_e32 v1, 0, v2, vcc
	s_waitcnt vmcnt(6)
	v_cndmask_b32_e32 v2, 0, v3, vcc
	s_waitcnt vmcnt(5)
	v_cndmask_b32_e32 v3, 0, v4, vcc
	s_waitcnt vmcnt(4)
	v_cndmask_b32_e32 v4, 0, v5, vcc
	s_waitcnt vmcnt(3)
	v_cndmask_b32_e32 v5, 0, v6, vcc
	s_waitcnt vmcnt(2)
	v_cndmask_b32_e32 v6, 0, v7, vcc
	s_waitcnt vmcnt(1)
	v_cndmask_b32_e32 v7, 0, v8, vcc
	s_waitcnt vmcnt(0)
	v_cndmask_b32_e32 v0, 0, v0, vcc
	v_cvt_pk_bf16_f32 v31, v7, v0
	v_lshlrev_b32_e32 v0, 4, v32
	v_and_b32_e32 v0, 0xfffffc00, v0
	v_cvt_pk_bf16_f32 v28, v1, v2
	v_ashrrev_i32_e32 v1, 31, v0
	v_lshlrev_b32_e32 v2, 6, v32
	v_or_b32_e32 v155, v0, v9
	v_or_b32_e32 v0, v0, v9
	v_and_b32_e32 v2, 0xfffff000, v2
	v_lshlrev_b64 v[0:1], 7, v[0:1]
	v_lshl_or_b32 v153, v9, 2, v2
	v_lshl_or_b32 v0, v33, 4, v0
	v_cvt_pk_bf16_f32 v29, v3, v4
	v_cvt_pk_bf16_f32 v30, v5, v6
	v_sub_u32_e32 v154, 0, v153
	v_sub_u32_e32 v0, v155, v9
	v_lshlrev_b32_e32 v0, 7, v0
	v_lshl_add_u32 v0, v9, 4, v0
	v_lshl_add_u32 v0, v33, 9, v0
	v_mov_b32_e32 v1, 0
	v_lshl_add_u64 v[148:149], s[86:87], 0, v[0:1]
	v_readlane_b32 s8, v252, 26
	v_readlane_b32 s9, v252, 27
	v_readlane_b32 s10, v252, 28
	v_readlane_b32 s11, v252, 29
	v_readlane_b32 s12, v252, 30
	v_readlane_b32 s13, v252, 31
	v_readlane_b32 s14, v252, 32
	v_readlane_b32 s15, v252, 33
	v_readlane_b32 s16, v252, 34
	v_readlane_b32 s17, v252, 35
	v_readlane_b32 s18, v252, 36
	v_readlane_b32 s19, v252, 37
	s_branch .LBB0_892

.LBB0_892:
	v_lshl_add_u64 v[36:37], v[148:149], 0, s[4:5]
	s_nop 0
	v_add_co_u32_e32 v4, vcc, 0xe300000, v36
	s_nop 1
	v_addc_co_u32_e32 v5, vcc, 0, v37, vcc
	global_load_dwordx4 v[0:3], v[4:5], off
	global_load_dwordx4 v[32:35], v[4:5], off offset:1024
	global_load_dwordx4 v[40:43], v[4:5], off offset:2048
	v_add_co_u32_e32 v6, vcc, 0xe301000, v36
	global_load_dwordx4 v[156:159], v[4:5], off offset:3072
	s_nop 0
	v_addc_co_u32_e32 v7, vcc, 0, v37, vcc
	v_add_co_u32_e32 v4, vcc, 0xe302000, v36
	global_load_dwordx4 v[140:143], v[6:7], off
	global_load_dwordx4 v[136:139], v[6:7], off offset:1024
	global_load_dwordx4 v[132:135], v[6:7], off offset:2048
	global_load_dwordx4 v[128:131], v[6:7], off offset:3072
	v_addc_co_u32_e32 v5, vcc, 0, v37, vcc
	v_add_co_u32_e32 v6, vcc, 0xe303000, v36
	global_load_dwordx4 v[124:127], v[4:5], off
	global_load_dwordx4 v[120:123], v[4:5], off offset:1024
	global_load_dwordx4 v[116:119], v[4:5], off offset:2048
	global_load_dwordx4 v[112:115], v[4:5], off offset:3072
	v_addc_co_u32_e32 v7, vcc, 0, v37, vcc
	v_add_co_u32_e32 v4, vcc, 0xe304000, v36
	global_load_dwordx4 v[108:111], v[6:7], off
	global_load_dwordx4 v[104:107], v[6:7], off offset:1024
	global_load_dwordx4 v[100:103], v[6:7], off offset:2048
	global_load_dwordx4 v[96:99], v[6:7], off offset:3072
	v_addc_co_u32_e32 v5, vcc, 0, v37, vcc
	v_add_co_u32_e32 v6, vcc, 0xe305000, v36
	global_load_dwordx4 v[92:95], v[4:5], off
	global_load_dwordx4 v[88:91], v[4:5], off offset:1024
	global_load_dwordx4 v[84:87], v[4:5], off offset:2048
	global_load_dwordx4 v[80:83], v[4:5], off offset:3072
	v_addc_co_u32_e32 v7, vcc, 0, v37, vcc
	global_load_dwordx4 v[76:79], v[6:7], off
	global_load_dwordx4 v[68:71], v[6:7], off offset:1024
	global_load_dwordx4 v[56:59], v[6:7], off offset:2048
	global_load_dwordx4 v[48:51], v[6:7], off offset:3072
	v_add_co_u32_e32 v38, vcc, 0xe306000, v36
	s_waitcnt vmcnt(23)
	v_mfma_f32_32x32x16_bf16 v[0:15], v[16:19], v[0:3], 0
	v_addc_co_u32_e32 v39, vcc, 0, v37, vcc
	v_add_co_u32_e32 v44, vcc, 0xe307000, v36
	global_load_dwordx4 v[72:75], v[38:39], off
	global_load_dwordx4 v[60:63], v[38:39], off offset:1024
	v_addc_co_u32_e32 v45, vcc, 0, v37, vcc
	s_waitcnt vmcnt(24)
	v_mfma_f32_32x32x16_bf16 v[0:15], v[20:23], v[32:35], v[0:15]
	global_load_dwordx4 v[64:67], v[38:39], off offset:2048
	global_load_dwordx4 v[52:55], v[38:39], off offset:3072
	s_nop 0
	global_load_dwordx4 v[36:39], v[44:45], off
	global_load_dwordx4 v[32:35], v[44:45], off offset:1024
	s_waitcnt vmcnt(27)
	v_mfma_f32_32x32x16_bf16 v[0:15], v[24:27], v[40:43], v[0:15]
	global_load_dwordx4 v[40:43], v[44:45], off offset:2048
	s_nop 0
	global_load_dwordx4 v[44:47], v[44:45], off offset:3072
	s_waitcnt vmcnt(28)
	v_mfma_f32_32x32x16_bf16 v[0:15], v[28:31], v[156:159], v[0:15]
	v_add_u32_e32 v157, 16, v153
	v_add_u32_e32 v156, 16, v154
	s_and_saveexec_b64 s[6:7], s[0:1]
	s_cbranch_execz .LBB0_894
	s_nop 7
	v_cvt_f32_i32_e32 v4, v155
	v_mul_f32_e32 v4, 0xb9000400, v4
	v_mul_f32_e64 v5, |v144|, v4
	v_mul_f32_e64 v4, |v147|, v4
	v_mul_f32_e32 v5, 0x3fb8aa3b, v5
	v_mul_f32_e32 v4, 0x3fb8aa3b, v4
	v_exp_f32_e32 v5, v5
	v_exp_f32_e32 v4, v4
	v_mul_f32_e32 v0, v5, v0
	v_mul_f32_e32 v1, v4, v1
	v_mul_f32_e32 v2, v5, v2
	ds_write_b32 v157, v0
	ds_write_b32 v156, v1 offset:65532
	v_add_u32_e32 v0, 0x10000, v157
	ds_write_b32 v0, v2
	v_mul_f32_e32 v0, v4, v3
	v_add_u32_e32 v1, 0x1fffc, v156
	ds_write_b32 v1, v0
